# scan phase: K^T staging writes paired across lanes (DPP row_ror:8 + v_cvt_pk_bf16_f32, 4 dword LDS writes per chunk instead of 8 two-byte writes), on top of conv move
# baseline (speedup 1.0000x reference)
.LBB0_640:
	s_mov_b32 vcc_lo, 0xff00ff00
	s_mov_b32 vcc_hi, 0xff00ff00
	s_nop 1
	v_mov_b32_e32 v204, 0x83e
	v_cndmask_b32_e32 v204, 0, v204, vcc
	s_waitcnt vmcnt(6)
	ds_write_b128 v108, v[28:31] offset:33792
	v_lshlrev_b32_e32 v168, 16, v48
	v_and_b32_e32 v169, 0xffff0000, v48
	v_lshlrev_b32_e32 v170, 16, v49
	v_and_b32_e32 v171, 0xffff0000, v49
	v_lshlrev_b32_e32 v172, 16, v50
	v_and_b32_e32 v173, 0xffff0000, v50
	v_lshlrev_b32_e32 v174, 16, v51
	v_and_b32_e32 v175, 0xffff0000, v51
	v_mul_f32_e32 v168, v109, v168
	v_mul_f32_e32 v169, v109, v169
	v_mul_f32_e32 v170, v109, v170
	v_mul_f32_e32 v171, v109, v171
	v_mul_f32_e32 v172, v109, v172
	v_mul_f32_e32 v173, v109, v173
	v_mul_f32_e32 v174, v109, v174
	v_mul_f32_e32 v175, v109, v175
	v_add_u32_e32 v205, v135, v204
	s_nop 0
	v_mov_b32_dpp v176, v168 row_ror:8 row_mask:0xf bank_mask:0xf
	v_mov_b32_dpp v177, v169 row_ror:8 row_mask:0xf bank_mask:0xf
	v_mov_b32_dpp v178, v170 row_ror:8 row_mask:0xf bank_mask:0xf
	v_mov_b32_dpp v179, v171 row_ror:8 row_mask:0xf bank_mask:0xf
	v_mov_b32_dpp v180, v172 row_ror:8 row_mask:0xf bank_mask:0xf
	v_mov_b32_dpp v181, v173 row_ror:8 row_mask:0xf bank_mask:0xf
	v_mov_b32_dpp v182, v174 row_ror:8 row_mask:0xf bank_mask:0xf
	v_mov_b32_dpp v183, v175 row_ror:8 row_mask:0xf bank_mask:0xf
	v_cvt_pk_bf16_f32 v184, v168, v176
	v_cvt_pk_bf16_f32 v185, v169, v177
	v_cvt_pk_bf16_f32 v186, v170, v178
	v_cvt_pk_bf16_f32 v187, v171, v179
	v_cvt_pk_bf16_f32 v188, v180, v172
	v_cvt_pk_bf16_f32 v189, v181, v173
	v_cvt_pk_bf16_f32 v190, v182, v174
	v_cvt_pk_bf16_f32 v191, v183, v175
	v_cndmask_b32_e32 v184, v184, v188, vcc
	v_cndmask_b32_e32 v185, v185, v189, vcc
	v_cndmask_b32_e32 v186, v186, v190, vcc
	v_cndmask_b32_e32 v187, v187, v191, vcc
	ds_write2_b32 v205, v184, v185 offset0:0 offset1:132
	ds_write_b32 v205, v186 offset:1056
	ds_write_b32 v205, v187 offset:1584
	s_waitcnt vmcnt(4)
	ds_write_b128 v108, v[56:59] offset:42240
	v_lshlrev_b32_e32 v168, 16, v64
	v_and_b32_e32 v169, 0xffff0000, v64
	v_lshlrev_b32_e32 v170, 16, v65
	v_and_b32_e32 v171, 0xffff0000, v65
	v_lshlrev_b32_e32 v172, 16, v66
	v_and_b32_e32 v173, 0xffff0000, v66
	v_lshlrev_b32_e32 v174, 16, v67
	v_and_b32_e32 v175, 0xffff0000, v67
	v_mul_f32_e32 v168, v111, v168
	v_mul_f32_e32 v169, v111, v169
	v_mul_f32_e32 v170, v111, v170
	v_mul_f32_e32 v171, v111, v171
	v_mul_f32_e32 v172, v111, v172
	v_mul_f32_e32 v173, v111, v173
	v_mul_f32_e32 v174, v111, v174
	v_mul_f32_e32 v175, v111, v175
	v_add_u32_e32 v205, v136, v204
	s_nop 0
	v_mov_b32_dpp v176, v168 row_ror:8 row_mask:0xf bank_mask:0xf
	v_mov_b32_dpp v177, v169 row_ror:8 row_mask:0xf bank_mask:0xf
	v_mov_b32_dpp v178, v170 row_ror:8 row_mask:0xf bank_mask:0xf
	v_mov_b32_dpp v179, v171 row_ror:8 row_mask:0xf bank_mask:0xf
	v_mov_b32_dpp v180, v172 row_ror:8 row_mask:0xf bank_mask:0xf
	v_mov_b32_dpp v181, v173 row_ror:8 row_mask:0xf bank_mask:0xf
	v_mov_b32_dpp v182, v174 row_ror:8 row_mask:0xf bank_mask:0xf
	v_mov_b32_dpp v183, v175 row_ror:8 row_mask:0xf bank_mask:0xf
	v_cvt_pk_bf16_f32 v184, v168, v176
	v_cvt_pk_bf16_f32 v185, v169, v177
	v_cvt_pk_bf16_f32 v186, v170, v178
	v_cvt_pk_bf16_f32 v187, v171, v179
	v_cvt_pk_bf16_f32 v188, v180, v172
	v_cvt_pk_bf16_f32 v189, v181, v173
	v_cvt_pk_bf16_f32 v190, v182, v174
	v_cvt_pk_bf16_f32 v191, v183, v175
	v_cndmask_b32_e32 v184, v184, v188, vcc
	v_cndmask_b32_e32 v185, v185, v189, vcc
	v_cndmask_b32_e32 v186, v186, v190, vcc
	v_cndmask_b32_e32 v187, v187, v191, vcc
	ds_write2_b32 v205, v184, v185 offset0:0 offset1:132
	ds_write_b32 v205, v186 offset:1056
	ds_write_b32 v205, v187 offset:1584
	s_waitcnt vmcnt(2)
; __device__ __forceinline__ void ret_scan_mfma(const int tid, const int bid, LAS unsigned char* lds, const bf16* K, const bf16* VT, bf16* ST) {
;     ...
;         R1_STORE(vrB, krB, 1);
;         __syncthreads();
	ds_write_b128 v108, v[76:79] offset:50688
	v_lshlrev_b32_e32 v168, 16, v80
	v_and_b32_e32 v169, 0xffff0000, v80
	v_lshlrev_b32_e32 v170, 16, v81
	v_and_b32_e32 v171, 0xffff0000, v81
	v_lshlrev_b32_e32 v172, 16, v82
	v_and_b32_e32 v173, 0xffff0000, v82
	v_lshlrev_b32_e32 v174, 16, v83
	v_and_b32_e32 v175, 0xffff0000, v83
	v_mul_f32_e32 v168, v113, v168
	v_mul_f32_e32 v169, v113, v169
	v_mul_f32_e32 v170, v113, v170
	v_mul_f32_e32 v171, v113, v171
	v_mul_f32_e32 v172, v113, v172
	v_mul_f32_e32 v173, v113, v173
	v_mul_f32_e32 v174, v113, v174
	v_mul_f32_e32 v175, v113, v175
	v_add_u32_e32 v205, v137, v204
	s_nop 0
	v_mov_b32_dpp v176, v168 row_ror:8 row_mask:0xf bank_mask:0xf
	v_mov_b32_dpp v177, v169 row_ror:8 row_mask:0xf bank_mask:0xf
	v_mov_b32_dpp v178, v170 row_ror:8 row_mask:0xf bank_mask:0xf
	v_mov_b32_dpp v179, v171 row_ror:8 row_mask:0xf bank_mask:0xf
	v_mov_b32_dpp v180, v172 row_ror:8 row_mask:0xf bank_mask:0xf
	v_mov_b32_dpp v181, v173 row_ror:8 row_mask:0xf bank_mask:0xf
	v_mov_b32_dpp v182, v174 row_ror:8 row_mask:0xf bank_mask:0xf
	v_mov_b32_dpp v183, v175 row_ror:8 row_mask:0xf bank_mask:0xf
	v_cvt_pk_bf16_f32 v184, v168, v176
	v_cvt_pk_bf16_f32 v185, v169, v177
	v_cvt_pk_bf16_f32 v186, v170, v178
	v_cvt_pk_bf16_f32 v187, v171, v179
	v_cvt_pk_bf16_f32 v188, v180, v172
	v_cvt_pk_bf16_f32 v189, v181, v173
	v_cvt_pk_bf16_f32 v190, v182, v174
	v_cvt_pk_bf16_f32 v191, v183, v175
	v_cndmask_b32_e32 v184, v184, v188, vcc
	v_cndmask_b32_e32 v185, v185, v189, vcc
	v_cndmask_b32_e32 v186, v186, v190, vcc
	v_cndmask_b32_e32 v187, v187, v191, vcc
	ds_write2_b32 v205, v184, v185 offset0:0 offset1:132
	ds_write_b32 v205, v186 offset:1056
	ds_write_b32 v205, v187 offset:1584
	s_waitcnt vmcnt(0)
	ds_write_b128 v108, v[88:91] offset:59136
	v_lshlrev_b32_e32 v168, 16, v92
	v_and_b32_e32 v169, 0xffff0000, v92
	v_lshlrev_b32_e32 v170, 16, v93
	v_and_b32_e32 v171, 0xffff0000, v93
	v_lshlrev_b32_e32 v172, 16, v94
	v_and_b32_e32 v173, 0xffff0000, v94
	v_lshlrev_b32_e32 v174, 16, v95
	v_and_b32_e32 v175, 0xffff0000, v95
	v_mul_f32_e32 v168, v115, v168
	v_mul_f32_e32 v169, v115, v169
	v_mul_f32_e32 v170, v115, v170
	v_mul_f32_e32 v171, v115, v171
	v_mul_f32_e32 v172, v115, v172
	v_mul_f32_e32 v173, v115, v173
	v_mul_f32_e32 v174, v115, v174
	v_mul_f32_e32 v175, v115, v175
	v_add_u32_e32 v205, v138, v204
	s_nop 0
	v_mov_b32_dpp v176, v168 row_ror:8 row_mask:0xf bank_mask:0xf
	v_mov_b32_dpp v177, v169 row_ror:8 row_mask:0xf bank_mask:0xf
	v_mov_b32_dpp v178, v170 row_ror:8 row_mask:0xf bank_mask:0xf
	v_mov_b32_dpp v179, v171 row_ror:8 row_mask:0xf bank_mask:0xf
	v_mov_b32_dpp v180, v172 row_ror:8 row_mask:0xf bank_mask:0xf
	v_mov_b32_dpp v181, v173 row_ror:8 row_mask:0xf bank_mask:0xf
	v_mov_b32_dpp v182, v174 row_ror:8 row_mask:0xf bank_mask:0xf
	v_mov_b32_dpp v183, v175 row_ror:8 row_mask:0xf bank_mask:0xf
	v_cvt_pk_bf16_f32 v184, v168, v176
	v_cvt_pk_bf16_f32 v185, v169, v177
	v_cvt_pk_bf16_f32 v186, v170, v178
	v_cvt_pk_bf16_f32 v187, v171, v179
	v_cvt_pk_bf16_f32 v188, v180, v172
	v_cvt_pk_bf16_f32 v189, v181, v173
	v_cvt_pk_bf16_f32 v190, v182, v174
	v_cvt_pk_bf16_f32 v191, v183, v175
	v_cndmask_b32_e32 v184, v184, v188, vcc
	v_cndmask_b32_e32 v185, v185, v189, vcc
	v_cndmask_b32_e32 v186, v186, v190, vcc
	v_cndmask_b32_e32 v187, v187, v191, vcc
	ds_write2_b32 v205, v184, v185 offset0:0 offset1:132
	ds_write_b32 v205, v186 offset:1056
	ds_write_b32 v205, v187 offset:1584
	s_cmp_gt_u32 s4, 28
	s_waitcnt lgkmcnt(0)
	s_barrier
	s_cbranch_scc0 .LBB0_643
	s_and_b64 vcc, exec, s[40:41]
	s_cbranch_vccz .LBB0_644

; __device__ __forceinline__ void ret_scan_mfma(const int tid, const int bid, LAS unsigned char* lds, const bf16* K, const bf16* VT, bf16* ST) {
;     ...
;         if (c2 + 2 < 32) R1_STORE(vrA, krA, 0);
;         __syncthreads();
.LBB0_645:
	s_mov_b32 vcc_lo, 0xff00ff00
	s_mov_b32 vcc_hi, 0xff00ff00
	s_nop 1
	v_mov_b32_e32 v204, 0x83e
	v_cndmask_b32_e32 v204, 0, v204, vcc
	ds_write_b128 v108, v[16:19]
	v_lshlrev_b32_e32 v168, 16, v20
	v_and_b32_e32 v169, 0xffff0000, v20
	v_lshlrev_b32_e32 v170, 16, v21
	v_and_b32_e32 v171, 0xffff0000, v21
	v_lshlrev_b32_e32 v172, 16, v22
	v_and_b32_e32 v173, 0xffff0000, v22
	v_lshlrev_b32_e32 v174, 16, v23
	v_and_b32_e32 v175, 0xffff0000, v23
	v_mul_f32_e32 v168, v109, v168
	v_mul_f32_e32 v169, v109, v169
	v_mul_f32_e32 v170, v109, v170
	v_mul_f32_e32 v171, v109, v171
	v_mul_f32_e32 v172, v109, v172
	v_mul_f32_e32 v173, v109, v173
	v_mul_f32_e32 v174, v109, v174
	v_mul_f32_e32 v175, v109, v175
	v_add_u32_e32 v205, v110, v204
	s_nop 0
	v_mov_b32_dpp v176, v168 row_ror:8 row_mask:0xf bank_mask:0xf
	v_mov_b32_dpp v177, v169 row_ror:8 row_mask:0xf bank_mask:0xf
	v_mov_b32_dpp v178, v170 row_ror:8 row_mask:0xf bank_mask:0xf
	v_mov_b32_dpp v179, v171 row_ror:8 row_mask:0xf bank_mask:0xf
	v_mov_b32_dpp v180, v172 row_ror:8 row_mask:0xf bank_mask:0xf
	v_mov_b32_dpp v181, v173 row_ror:8 row_mask:0xf bank_mask:0xf
	v_mov_b32_dpp v182, v174 row_ror:8 row_mask:0xf bank_mask:0xf
	v_mov_b32_dpp v183, v175 row_ror:8 row_mask:0xf bank_mask:0xf
	v_cvt_pk_bf16_f32 v184, v168, v176
	v_cvt_pk_bf16_f32 v185, v169, v177
	v_cvt_pk_bf16_f32 v186, v170, v178
	v_cvt_pk_bf16_f32 v187, v171, v179
	v_cvt_pk_bf16_f32 v188, v180, v172
	v_cvt_pk_bf16_f32 v189, v181, v173
	v_cvt_pk_bf16_f32 v190, v182, v174
	v_cvt_pk_bf16_f32 v191, v183, v175
	v_cndmask_b32_e32 v184, v184, v188, vcc
	v_cndmask_b32_e32 v185, v185, v189, vcc
	v_cndmask_b32_e32 v186, v186, v190, vcc
	v_cndmask_b32_e32 v187, v187, v191, vcc
	ds_write2_b32 v205, v184, v185 offset0:0 offset1:132
	ds_write_b32 v205, v186 offset:1056
	ds_write_b32 v205, v187 offset:1584
	ds_write_b128 v108, v[24:27] offset:8448
	v_lshlrev_b32_e32 v168, 16, v52
	v_and_b32_e32 v169, 0xffff0000, v52
	v_lshlrev_b32_e32 v170, 16, v53
	v_and_b32_e32 v171, 0xffff0000, v53
	v_lshlrev_b32_e32 v172, 16, v54
	v_and_b32_e32 v173, 0xffff0000, v54
	v_lshlrev_b32_e32 v174, 16, v55
	v_and_b32_e32 v175, 0xffff0000, v55
	v_mul_f32_e32 v168, v111, v168
	v_mul_f32_e32 v169, v111, v169
	v_mul_f32_e32 v170, v111, v170
	v_mul_f32_e32 v171, v111, v171
	v_mul_f32_e32 v172, v111, v172
	v_mul_f32_e32 v173, v111, v173
	v_mul_f32_e32 v174, v111, v174
	v_mul_f32_e32 v175, v111, v175
	v_add_u32_e32 v205, v112, v204
	s_nop 0
	v_mov_b32_dpp v176, v168 row_ror:8 row_mask:0xf bank_mask:0xf
	v_mov_b32_dpp v177, v169 row_ror:8 row_mask:0xf bank_mask:0xf
	v_mov_b32_dpp v178, v170 row_ror:8 row_mask:0xf bank_mask:0xf
	v_mov_b32_dpp v179, v171 row_ror:8 row_mask:0xf bank_mask:0xf
	v_mov_b32_dpp v180, v172 row_ror:8 row_mask:0xf bank_mask:0xf
	v_mov_b32_dpp v181, v173 row_ror:8 row_mask:0xf bank_mask:0xf
	v_mov_b32_dpp v182, v174 row_ror:8 row_mask:0xf bank_mask:0xf
	v_mov_b32_dpp v183, v175 row_ror:8 row_mask:0xf bank_mask:0xf
	v_cvt_pk_bf16_f32 v184, v168, v176
	v_cvt_pk_bf16_f32 v185, v169, v177
	v_cvt_pk_bf16_f32 v186, v170, v178
	v_cvt_pk_bf16_f32 v187, v171, v179
	v_cvt_pk_bf16_f32 v188, v180, v172
	v_cvt_pk_bf16_f32 v189, v181, v173
	v_cvt_pk_bf16_f32 v190, v182, v174
	v_cvt_pk_bf16_f32 v191, v183, v175
	v_cndmask_b32_e32 v184, v184, v188, vcc
	v_cndmask_b32_e32 v185, v185, v189, vcc
	v_cndmask_b32_e32 v186, v186, v190, vcc
	v_cndmask_b32_e32 v187, v187, v191, vcc
	ds_write2_b32 v205, v184, v185 offset0:0 offset1:132
	ds_write_b32 v205, v186 offset:1056
	ds_write_b32 v205, v187 offset:1584
	ds_write_b128 v108, v[72:75] offset:16896
	v_lshlrev_b32_e32 v168, 16, v60
	v_and_b32_e32 v169, 0xffff0000, v60
	v_lshlrev_b32_e32 v170, 16, v61
	v_and_b32_e32 v171, 0xffff0000, v61
	v_lshlrev_b32_e32 v172, 16, v62
	v_and_b32_e32 v173, 0xffff0000, v62
	v_lshlrev_b32_e32 v174, 16, v63
	v_and_b32_e32 v175, 0xffff0000, v63
	v_mul_f32_e32 v168, v113, v168
	v_mul_f32_e32 v169, v113, v169
	v_mul_f32_e32 v170, v113, v170
	v_mul_f32_e32 v171, v113, v171
	v_mul_f32_e32 v172, v113, v172
	v_mul_f32_e32 v173, v113, v173
	v_mul_f32_e32 v174, v113, v174
	v_mul_f32_e32 v175, v113, v175
	v_add_u32_e32 v205, v114, v204
	s_nop 0
	v_mov_b32_dpp v176, v168 row_ror:8 row_mask:0xf bank_mask:0xf
	v_mov_b32_dpp v177, v169 row_ror:8 row_mask:0xf bank_mask:0xf
	v_mov_b32_dpp v178, v170 row_ror:8 row_mask:0xf bank_mask:0xf
	v_mov_b32_dpp v179, v171 row_ror:8 row_mask:0xf bank_mask:0xf
	v_mov_b32_dpp v180, v172 row_ror:8 row_mask:0xf bank_mask:0xf
	v_mov_b32_dpp v181, v173 row_ror:8 row_mask:0xf bank_mask:0xf
	v_mov_b32_dpp v182, v174 row_ror:8 row_mask:0xf bank_mask:0xf
	v_mov_b32_dpp v183, v175 row_ror:8 row_mask:0xf bank_mask:0xf
	v_cvt_pk_bf16_f32 v184, v168, v176
	v_cvt_pk_bf16_f32 v185, v169, v177
	v_cvt_pk_bf16_f32 v186, v170, v178
	v_cvt_pk_bf16_f32 v187, v171, v179
	v_cvt_pk_bf16_f32 v188, v180, v172
	v_cvt_pk_bf16_f32 v189, v181, v173
	v_cvt_pk_bf16_f32 v190, v182, v174
	v_cvt_pk_bf16_f32 v191, v183, v175
	v_cndmask_b32_e32 v184, v184, v188, vcc
	v_cndmask_b32_e32 v185, v185, v189, vcc
	v_cndmask_b32_e32 v186, v186, v190, vcc
	v_cndmask_b32_e32 v187, v187, v191, vcc
	ds_write2_b32 v205, v184, v185 offset0:0 offset1:132
	ds_write_b32 v205, v186 offset:1056
	ds_write_b32 v205, v187 offset:1584
	ds_write_b128 v108, v[68:71] offset:25344
	v_lshlrev_b32_e32 v168, 16, v84
	v_and_b32_e32 v169, 0xffff0000, v84
	v_lshlrev_b32_e32 v170, 16, v85
	v_and_b32_e32 v171, 0xffff0000, v85
	v_lshlrev_b32_e32 v172, 16, v86
	v_and_b32_e32 v173, 0xffff0000, v86
	v_lshlrev_b32_e32 v174, 16, v87
	v_and_b32_e32 v175, 0xffff0000, v87
	v_mul_f32_e32 v168, v115, v168
	v_mul_f32_e32 v169, v115, v169
	v_mul_f32_e32 v170, v115, v170
	v_mul_f32_e32 v171, v115, v171
	v_mul_f32_e32 v172, v115, v172
	v_mul_f32_e32 v173, v115, v173
	v_mul_f32_e32 v174, v115, v174
	v_mul_f32_e32 v175, v115, v175
	v_add_u32_e32 v205, v116, v204
	s_nop 0
	v_mov_b32_dpp v176, v168 row_ror:8 row_mask:0xf bank_mask:0xf
	v_mov_b32_dpp v177, v169 row_ror:8 row_mask:0xf bank_mask:0xf
	v_mov_b32_dpp v178, v170 row_ror:8 row_mask:0xf bank_mask:0xf
	v_mov_b32_dpp v179, v171 row_ror:8 row_mask:0xf bank_mask:0xf
	v_mov_b32_dpp v180, v172 row_ror:8 row_mask:0xf bank_mask:0xf
	v_mov_b32_dpp v181, v173 row_ror:8 row_mask:0xf bank_mask:0xf
	v_mov_b32_dpp v182, v174 row_ror:8 row_mask:0xf bank_mask:0xf
	v_mov_b32_dpp v183, v175 row_ror:8 row_mask:0xf bank_mask:0xf
	v_cvt_pk_bf16_f32 v184, v168, v176
	v_cvt_pk_bf16_f32 v185, v169, v177
	v_cvt_pk_bf16_f32 v186, v170, v178
	v_cvt_pk_bf16_f32 v187, v171, v179
	v_cvt_pk_bf16_f32 v188, v180, v172
	v_cvt_pk_bf16_f32 v189, v181, v173
	v_cvt_pk_bf16_f32 v190, v182, v174
	v_cvt_pk_bf16_f32 v191, v183, v175
	v_cndmask_b32_e32 v184, v184, v188, vcc
	v_cndmask_b32_e32 v185, v185, v189, vcc
	v_cndmask_b32_e32 v186, v186, v190, vcc
	v_cndmask_b32_e32 v187, v187, v191, vcc
	ds_write2_b32 v205, v184, v185 offset0:0 offset1:132
	ds_write_b32 v205, v186 offset:1056
	ds_write_b32 v205, v187 offset:1584
	s_branch .LBB0_635
